# decode sequential-scan tasks also moved off the scan-block worker waves (only decode attention stays there)
# baseline (speedup 1.0000x reference)
; #define LAS __attribute__((address_space(3)))
; #define REP(k) for (int rep_ = 0; rep_ < 1 + ((PROBE_MASK >> (k)) & 1); ++rep_)
; #define PHASE_IDS() int tid_p = threadIdx.x; asm volatile("" : "+v"(tid_p)); const int lane = tid_p & 63, wave = __builtin_amdgcn_readfirstlane(tid_p >> 6), gw = bx * 8 + wave; const size_t gt = (size_t)bx * 512 + tid_p; (void)lane; (void)wave; (void)gw; (void)gt
; __global__ void __launch_bounds__(512, 2) mega(Args a) {
;     ...
;         if (IN(pb + 3)) REP(3) {
;             PHASE_IDS();
;             if (tid_p < 16) ((volatile LAS unsigned*)(lds + SCAN_FLAGS_OFF))[tid_p] = 0u;
;             __syncthreads();
;             const int nsb = G < 128 ? G : 128;
;             const int nrole = SCAN_LOADERS ? 4 : 1;
;             const bool scan_block = bx < nsb;
;             if (scan_block && wave < nrole) {
;                 REP(13) for (int id = bx; id < 128; id += G) {
;                     if (tid_p < 16) {}
;                     if (wave == 0) {
;                         if (id < 64) gla_scan_task(p, l, id >> 5, (id >> 3) & 3, id & 7, lds, lane);
;                         else delta_scan_task(p, l, (id - 64) >> 5, ((id - 64) >> 2) & 7, (id - 64) & 3, lds, lane);
;                     } else scan_loader(p, id, wave - 1, lds, lane);
;                 }
;             } else {
;                 const int wpb = 8 - nrole;
;                 const int widx = scan_block ? bx * wpb + (wave - nrole) : nsb * wpb + (bx - nsb) * 8 + wave, nwork = nsb * wpb + (G - nsb) * 8;
;                 REP(14) for (int task = widx; task < 8192; task += nwork) scan_task(p, l, 512 + task, lane);
.LBB0_1172:
	s_andn2_b64 vcc, exec, s[0:1]
	s_cbranch_vccnz .LBB0_1608
	v_mov_b32_e32 v178, v0
	s_nop 0
	v_readfirstlane_b32 s92, v178
	v_cmp_gt_i32_e32 vcc, 16, v178
	s_and_saveexec_b64 s[0:1], vcc
	v_lshl_add_u32 v1, v178, 2, 0
	ds_write_b32 v1, v163 offset:13312
	s_or_b64 exec, exec, s[0:1]
	v_readlane_b32 s0, v254, 63
	s_lshl_b32 s54, s0, 4
	s_ashr_i32 s55, s92, 6
	v_readlane_b32 s1, v248, 0
	s_cmp_lt_i32 s55, 4
	v_readlane_b32 s4, v252, 58
	s_cselect_b64 s[0:1], -1, 0
	v_readlane_b32 s5, v252, 59
	s_and_b64 s[0:1], s[4:5], s[0:1]
	v_and_b32_e32 v161, 63, v178
	s_andn2_b64 vcc, exec, s[0:1]
	s_mov_b64 s[0:1], -1
	s_waitcnt vmcnt(0) lgkmcnt(0)
	s_barrier
	s_cbranch_vccz .LBB0_1422
	v_readlane_b32 s0, v253, 54
	s_add_i32 s93, s0, s55
	s_cmpk_lt_i32 s93, 0x200
	v_readlane_b32 s6, v252, 3
	s_cbranch_scc1 .LBB0_1199
	v_lshrrev_b32_e32 v2, 3, v161
	v_readlane_b32 s8, v254, 3
	v_lshlrev_b32_e32 v162, 6, v2
	v_readlane_b32 s9, v254, 4
	v_readlane_b32 s10, v254, 5
	v_readlane_b32 s11, v254, 6
	v_readlane_b32 s12, v254, 7
	v_readlane_b32 s13, v254, 8
	v_readlane_b32 s14, v254, 9
	v_readlane_b32 s15, v254, 10
	v_readlane_b32 s16, v254, 11
	v_readlane_b32 s17, v254, 12
	v_readlane_b32 s18, v254, 13
	v_readlane_b32 s19, v254, 14
	v_readlane_b32 s20, v254, 15
	v_readlane_b32 s21, v254, 16
	v_readlane_b32 s22, v254, 17
	v_readlane_b32 s23, v254, 18
	v_lshl_add_u64 v[124:125], s[8:9], 0, v[162:163]
	v_readlane_b32 s8, v249, 44
	v_readlane_b32 s9, v249, 45
	v_readlane_b32 s10, v249, 46
	v_readlane_b32 s11, v249, 47
	v_readlane_b32 s12, v249, 48
	v_readlane_b32 s22, v249, 58
	v_readlane_b32 s23, v249, 59
	v_readlane_b32 s0, v254, 63
	v_and_b32_e32 v1, 7, v178
	v_lshlrev_b32_e32 v123, 11, v2
	v_lshlrev_b32_e32 v122, 4, v2
	v_cmp_gt_u32_e64 s[38:39], 8, v161
	v_lshlrev_b32_e32 v179, 12, v2
	v_lshl_add_u64 v[126:127], s[22:23], 0, v[162:163]
	s_lshl_b32 s8, s0, 8
	s_lshl_b32 s9, s0, 7
	s_lshl_b32 s10, s55, 3
	v_readlane_b32 s11, v253, 55
	s_add_i32 s12, s93, 0xfffffe00
	v_readlane_b32 s13, v249, 49
	v_readlane_b32 s14, v249, 50
	v_readlane_b32 s15, v249, 51
	v_readlane_b32 s16, v249, 52
	v_readlane_b32 s17, v249, 53
	v_readlane_b32 s18, v249, 54
	v_readlane_b32 s19, v249, 55
	v_readlane_b32 s20, v249, 56
	v_readlane_b32 s21, v249, 57
	v_readlane_b32 s1, v248, 0
	s_branch .LBB0_1180
.LBB0_1178:
	s_or_b64 exec, exec, s[6:7]
	s_lshl_b64 s[0:1], s[0:1], 15
	v_or_b32_e32 v162, 0x100, v114
	v_mov_b32_e32 v115, v163
	v_or_b32_e32 v26, 0x200, v114
	v_mov_b32_e32 v27, v163
	v_or_b32_e32 v28, 0x300, v114
	v_mov_b32_e32 v29, v163
	v_mov_b32_e32 v107, v163
	v_mov_b32_e32 v109, v163
	v_mov_b32_e32 v111, v163
	v_mov_b32_e32 v113, v163
	v_mov_b32_e32 v129, v163
	v_mov_b32_e32 v131, v163
	v_mov_b32_e32 v133, v163
	v_mov_b32_e32 v135, v163
	v_mov_b32_e32 v137, v163
	v_mov_b32_e32 v139, v163
	v_mov_b32_e32 v141, v163
	v_mov_b32_e32 v143, v163
	s_waitcnt lgkmcnt(2)
	v_mov_b64_e32 v[4:5], 0x6bf8000
	v_mov_b64_e32 v[2:3], s[0:1]
	v_mov_b64_e32 v[30:31], v[162:163]
	v_readlane_b32 s6, v252, 3

; __device__ __forceinline__ void delta_task(const P& p, int l, int s, int h, int sl, int lane) {
;     ...
;         for (int i4 = 0; i4 < 4; ++i4)
; #pragma unroll
;             for (int e = 0; e < 4; ++e) S[4 * i4 + e] = fmaf(a, S[4 * i4 + e], k[t][i4][e] * u);
;         o[t] = a * qS + qk * u;
;     }
;     if (dkg == 0) {
; #pragma unroll
;         for (int t = 0; t < TD; ++t) p.OCRAW[(r0 + t) * 1024 + h * 128 + col] = o[t];
;     }
;     float* so = p.out + O_SDELTA + ((((size_t)l * 32 + (s - 2)) * 8 + h) * 128) * 128;
; #pragma unroll
;     for (int i = 0; i < 16; ++i) so[(size_t)(dkg * 16 + i) * 128 + col] = S[i];
.LBB0_1185:
	s_or_b64 exec, exec, s[4:5]
	s_lshl_b64 s[4:5], s[34:35], 14
	v_pk_mul_f32 v[16:17], v[16:17], v[40:41] op_sel_hi:[1,0]
	v_pk_mul_f32 v[14:15], v[14:15], v[40:41] op_sel_hi:[1,0]
	v_pk_mul_f32 v[12:13], v[12:13], v[40:41] op_sel_hi:[1,0]
	v_pk_mul_f32 v[10:11], v[10:11], v[40:41] op_sel_hi:[1,0]
	v_pk_mul_f32 v[8:9], v[8:9], v[40:41] op_sel_hi:[1,0]
	v_pk_mul_f32 v[6:7], v[6:7], v[40:41] op_sel_hi:[1,0]
	v_pk_mul_f32 v[4:5], v[4:5], v[40:41] op_sel_hi:[1,0]
	v_pk_mul_f32 v[2:3], v[2:3], v[40:41] op_sel_hi:[1,0]
	v_mov_b32_e32 v129, v163
	v_mov_b32_e32 v131, v163
	v_mov_b32_e32 v133, v163
	v_mov_b32_e32 v135, v163
	v_mov_b32_e32 v137, v163
	v_mov_b32_e32 v139, v163
	v_mov_b32_e32 v141, v163
	v_mov_b32_e32 v143, v163
	v_or_b32_e32 v30, 0x80, v162
	v_mov_b32_e32 v31, v163
	v_or_b32_e32 v26, 0x100, v162
	v_mov_b32_e32 v27, v163
	v_or_b32_e32 v28, 0x180, v162
	v_mov_b32_e32 v29, v163
	v_or_b32_e32 v106, 0x200, v162
	v_mov_b32_e32 v107, v163
	v_or_b32_e32 v108, 0x280, v162
	v_mov_b32_e32 v109, v163
	v_or_b32_e32 v110, 0x300, v162
	v_mov_b32_e32 v111, v163
	v_or_b32_e32 v112, 0x380, v162
	v_mov_b32_e32 v113, v163
	v_pk_fma_f32 v[24:25], v[38:39], v[54:55], v[16:17] op_sel_hi:[0,1,1]
	v_pk_fma_f32 v[22:23], v[38:39], v[52:53], v[14:15] op_sel_hi:[0,1,1]
	v_pk_fma_f32 v[20:21], v[38:39], v[32:33], v[12:13] op_sel_hi:[0,1,1]
	s_waitcnt lgkmcnt(0)
	v_pk_fma_f32 v[18:19], v[38:39], v[50:51], v[10:11] op_sel_hi:[0,1,1]
	v_pk_fma_f32 v[8:9], v[38:39], v[44:45], v[8:9] op_sel_hi:[0,1,1]
	v_pk_fma_f32 v[16:17], v[38:39], v[42:43], v[6:7] op_sel_hi:[0,1,1]
	v_pk_fma_f32 v[6:7], v[38:39], v[36:37], v[4:5] op_sel_hi:[0,1,1]
	v_pk_fma_f32 v[14:15], v[38:39], v[34:35], v[2:3] op_sel_hi:[0,1,1]
	s_mov_b64 s[0:1], 0
	v_mov_b64_e32 v[2:3], s[4:5]
	v_mov_b64_e32 v[114:115], v[162:163]
	v_readlane_b32 s6, v252, 3

; __device__ __forceinline__ void gla_task(const P& p, int l, int s, int h, int sl, int lane) {
;     ...
;     if (dkg == 0) {
; #pragma unroll
;         for (int t = 0; t < TD; ++t) p.OBRAW[(r0 + t) * 1024 + h * 256 + col] = o[t];
;     }
;     float* so = p.out + O_SGLA + ((((size_t)l * 32 + (s - 2)) * 4 + h) * 128) * 256;
; #pragma unroll
;     for (int i = 0; i < 16; ++i) so[(size_t)(dkg * 16 + i) * 256 + col] = S[i];
.LBB0_1189:
	s_or_b64 exec, exec, s[4:5]
	s_lshl_b64 s[0:1], s[34:35], 15
	v_or_b32_e32 v162, 0x100, v114
	v_mov_b32_e32 v115, v163
	v_or_b32_e32 v26, 0x200, v114
	v_mov_b32_e32 v27, v163
	v_or_b32_e32 v28, 0x300, v114
	v_mov_b32_e32 v29, v163
	v_mov_b32_e32 v107, v163
	v_mov_b32_e32 v109, v163
	v_mov_b32_e32 v111, v163
	v_mov_b32_e32 v113, v163
	v_mov_b32_e32 v129, v163
	v_mov_b32_e32 v131, v163
	v_mov_b32_e32 v133, v163
	v_mov_b32_e32 v135, v163
	v_mov_b32_e32 v137, v163
	v_mov_b32_e32 v139, v163
	v_mov_b32_e32 v141, v163
	v_mov_b32_e32 v143, v163
	s_mov_b64 s[4:5], 0x6bf8000
	s_waitcnt lgkmcnt(3)
	v_mov_b64_e32 v[2:3], s[0:1]
	v_mov_b64_e32 v[30:31], v[162:163]
	v_readlane_b32 s6, v252, 3

; __device__ __forceinline__ void delta_task(const P& p, int l, int s, int h, int sl, int lane) {
;     ...
;         for (int i4 = 0; i4 < 4; ++i4)
; #pragma unroll
;             for (int e = 0; e < 4; ++e) S[4 * i4 + e] = fmaf(a, S[4 * i4 + e], k[t][i4][e] * u);
;         o[t] = a * qS + qk * u;
;     }
;     if (dkg == 0) {
; #pragma unroll
;         for (int t = 0; t < TD; ++t) p.OCRAW[(r0 + t) * 1024 + h * 128 + col] = o[t];
;     }
;     float* so = p.out + O_SDELTA + ((((size_t)l * 32 + (s - 2)) * 8 + h) * 128) * 128;
; #pragma unroll
;     for (int i = 0; i < 16; ++i) so[(size_t)(dkg * 16 + i) * 128 + col] = S[i];
.LBB0_1194:
	s_or_b64 exec, exec, s[4:5]
	s_lshl_b64 s[0:1], s[0:1], 14
	v_pk_mul_f32 v[16:17], v[16:17], v[40:41] op_sel_hi:[1,0]
	v_pk_mul_f32 v[14:15], v[14:15], v[40:41] op_sel_hi:[1,0]
	v_pk_mul_f32 v[12:13], v[12:13], v[40:41] op_sel_hi:[1,0]
	v_pk_mul_f32 v[10:11], v[10:11], v[40:41] op_sel_hi:[1,0]
	v_pk_mul_f32 v[8:9], v[8:9], v[40:41] op_sel_hi:[1,0]
	v_pk_mul_f32 v[6:7], v[6:7], v[40:41] op_sel_hi:[1,0]
	v_pk_mul_f32 v[4:5], v[4:5], v[40:41] op_sel_hi:[1,0]
	v_pk_mul_f32 v[2:3], v[2:3], v[40:41] op_sel_hi:[1,0]
	v_mov_b32_e32 v129, v163
	v_mov_b32_e32 v131, v163
	v_mov_b32_e32 v133, v163
	v_mov_b32_e32 v135, v163
	v_mov_b32_e32 v137, v163
	v_mov_b32_e32 v139, v163
	v_mov_b32_e32 v141, v163
	v_mov_b32_e32 v143, v163
	v_or_b32_e32 v30, 0x80, v162
	v_mov_b32_e32 v31, v163
	v_or_b32_e32 v26, 0x100, v162
	v_mov_b32_e32 v27, v163
	v_or_b32_e32 v28, 0x180, v162
	v_mov_b32_e32 v29, v163
	v_or_b32_e32 v106, 0x200, v162
	v_mov_b32_e32 v107, v163
	v_or_b32_e32 v108, 0x280, v162
	v_mov_b32_e32 v109, v163
	v_or_b32_e32 v110, 0x300, v162
	v_mov_b32_e32 v111, v163
	v_or_b32_e32 v112, 0x380, v162
	v_mov_b32_e32 v113, v163
	v_pk_fma_f32 v[24:25], v[38:39], v[54:55], v[16:17] op_sel_hi:[0,1,1]
	v_pk_fma_f32 v[22:23], v[38:39], v[52:53], v[14:15] op_sel_hi:[0,1,1]
	v_pk_fma_f32 v[20:21], v[38:39], v[32:33], v[12:13] op_sel_hi:[0,1,1]
	s_waitcnt lgkmcnt(0)
	v_pk_fma_f32 v[18:19], v[38:39], v[50:51], v[10:11] op_sel_hi:[0,1,1]
	v_pk_fma_f32 v[8:9], v[38:39], v[44:45], v[8:9] op_sel_hi:[0,1,1]
	v_pk_fma_f32 v[16:17], v[38:39], v[42:43], v[6:7] op_sel_hi:[0,1,1]
	v_pk_fma_f32 v[6:7], v[38:39], v[36:37], v[4:5] op_sel_hi:[0,1,1]
	v_pk_fma_f32 v[14:15], v[38:39], v[34:35], v[2:3] op_sel_hi:[0,1,1]
	v_mov_b64_e32 v[4:5], 0xabf8000
	v_mov_b64_e32 v[2:3], s[0:1]
	v_mov_b64_e32 v[114:115], v[162:163]
	v_readlane_b32 s6, v252, 3
